# comb10 + grid barrier: waiting (non-leader) workgroups issue their L1 invalidate before spinning on the XCD generation word instead of after
# speedup vs baseline: 1.0189x; 1.0022x over previous
; __device__ __forceinline__ unsigned xb_ld(unsigned* p)              { return __hip_atomic_load(p, __ATOMIC_RELAXED, __HIP_MEMORY_SCOPE_AGENT); }
; __device__ __forceinline__ unsigned xb_add(unsigned* p, unsigned v) { return __hip_atomic_fetch_add(p, v, __ATOMIC_RELAXED, __HIP_MEMORY_SCOPE_AGENT); }
; #define XB_SPIN(cond, bar) do { unsigned _sp = 0; while (cond) { __builtin_amdgcn_s_sleep(1); \
;     if ((++_sp & 255u) == 0u) { if (xb_ld(&(bar)[XB_TMO])) break; if (_sp > XB_SPIN_CAP) { atomicAdd(&(bar)[XB_TMO], 1u); break; } } } } while (0)
; __device__ __forceinline__ void xcd_barrier(const XcdBarrier& b) {
;     ...
;         const unsigned old = xb_add(&bar[XB_XSUB(b.x)], 1u);
;         const unsigned gen = old / nloc;
;         if (old + 1u == (gen + 1u) * nloc) {
;             __builtin_amdgcn_fence(__ATOMIC_RELEASE, "agent");
;             asm volatile("s_waitcnt vmcnt(0)" ::: "memory");
;             const unsigned og = xb_add(&bar[XB_TOP], 1u);
;             const unsigned tg = og / nx;
;             if (og + 1u == (tg + 1u) * nx) xb_add(&bar[XB_TOPGEN], 1u);
;             else XB_SPIN(xb_ld(&bar[XB_TOPGEN]) == tg, bar);
;             __builtin_amdgcn_fence(__ATOMIC_ACQUIRE, "agent");
;             xb_add(&bar[XB_XGEN(b.x)], 1u);
;             asm volatile("s_waitcnt vmcnt(0)" ::: "memory");
;         } else {
;             XB_SPIN(xb_ld(&bar[XB_XGEN(b.x)]) == gen, bar);
;             __builtin_amdgcn_fence(__ATOMIC_ACQUIRE, "agent");
;             asm volatile("s_waitcnt vmcnt(0)" ::: "memory");
;         }
.LBB0_103:
	v_readlane_b32 s4, v248, 10
	s_lshl_b32 s4, s4, 8
	v_readlane_b32 s6, v248, 8
	v_readlane_b32 s7, v248, 9
	s_add_u32 s4, s6, s4
	s_addc_u32 s5, s7, 0
	v_mov_b32_e32 v2, 0x1000
	v_mov_b32_e32 v4, 1
	global_atomic_add v4, v2, v4, s[4:5] offset:1024 sc0
	v_cvt_f32_u32_e32 v2, v3
	v_sub_u32_e32 v5, 0, v3
	v_rcp_iflag_f32_e32 v2, v2
	s_nop 0
	v_mul_f32_e32 v2, 0x4f7ffffe, v2
	v_cvt_u32_f32_e32 v2, v2
	v_mul_lo_u32 v5, v5, v2
	v_mul_hi_u32 v5, v2, v5
	v_add_u32_e32 v2, v2, v5
	s_waitcnt vmcnt(0)
	v_mul_hi_u32 v2, v4, v2
	v_mul_lo_u32 v5, v2, v3
	v_sub_u32_e32 v5, v4, v5
	v_add_u32_e32 v6, 1, v2
	v_cmp_ge_u32_e32 vcc, v5, v3
	v_add_u32_e32 v4, 1, v4
	s_nop 0
	v_cndmask_b32_e32 v2, v2, v6, vcc
	v_sub_u32_e32 v6, v5, v3
	v_cndmask_b32_e32 v5, v5, v6, vcc
	v_add_u32_e32 v6, 1, v2
	v_cmp_ge_u32_e32 vcc, v5, v3
	s_nop 1
	v_cndmask_b32_e32 v2, v2, v6, vcc
	v_mul_lo_u32 v5, v3, v2
	v_add_u32_e32 v3, v5, v3
	v_cmp_ne_u32_e32 vcc, v4, v3
	s_and_saveexec_b64 s[6:7], vcc
	s_xor_b64 s[6:7], exec, s[6:7]
	s_cbranch_execz .LBB0_117
	s_waitcnt lgkmcnt(0)
	buffer_inv sc1
	v_mov_b32_e32 v1, 0x2000
	global_load_dword v1, v1, s[4:5] offset:1024 sc1
	s_add_u32 s14, s4, 0x2400
	s_addc_u32 s15, s5, 0
	s_waitcnt vmcnt(0)
	v_cmp_eq_u32_e32 vcc, v1, v2
	s_and_saveexec_b64 s[8:9], vcc
	s_cbranch_execz .LBB0_116
	s_add_u32 s12, s30, 0x3f52c200
	s_addc_u32 s13, s31, 0
	s_mov_b32 s27, 1
	s_mov_b64 s[16:17], 0
	v_mov_b32_e32 v1, 0
	s_branch .LBB0_107

; __device__ __forceinline__ unsigned xb_ld(unsigned* p)              { return __hip_atomic_load(p, __ATOMIC_RELAXED, __HIP_MEMORY_SCOPE_AGENT); }
; #define XB_SPIN(cond, bar) do { unsigned _sp = 0; while (cond) { __builtin_amdgcn_s_sleep(1); \
;     if ((++_sp & 255u) == 0u) { if (xb_ld(&(bar)[XB_TMO])) break; if (_sp > XB_SPIN_CAP) { atomicAdd(&(bar)[XB_TMO], 1u); break; } } } } while (0)
; __device__ __forceinline__ void xcd_barrier(const XcdBarrier& b) {
;     ...
;             XB_SPIN(xb_ld(&bar[XB_XGEN(b.x)]) == gen, bar);
;             __builtin_amdgcn_fence(__ATOMIC_ACQUIRE, "agent");
;             asm volatile("s_waitcnt vmcnt(0)" ::: "memory");
.LBB0_116:
	s_or_b64 exec, exec, s[8:9]
	s_waitcnt vmcnt(0)
	s_waitcnt vmcnt(0)

; __device__ __forceinline__ unsigned xb_ld(unsigned* p)              { return __hip_atomic_load(p, __ATOMIC_RELAXED, __HIP_MEMORY_SCOPE_AGENT); }
; __device__ __forceinline__ unsigned xb_add(unsigned* p, unsigned v) { return __hip_atomic_fetch_add(p, v, __ATOMIC_RELAXED, __HIP_MEMORY_SCOPE_AGENT); }
; #define XB_SPIN(cond, bar) do { unsigned _sp = 0; while (cond) { __builtin_amdgcn_s_sleep(1); \
;     if ((++_sp & 255u) == 0u) { if (xb_ld(&(bar)[XB_TMO])) break; if (_sp > XB_SPIN_CAP) { atomicAdd(&(bar)[XB_TMO], 1u); break; } } } } while (0)
; __device__ __forceinline__ void xcd_barrier(const XcdBarrier& b) {
;     ...
;         const unsigned old = xb_add(&bar[XB_XSUB(b.x)], 1u);
;         const unsigned gen = old / nloc;
;         if (old + 1u == (gen + 1u) * nloc) {
;             __builtin_amdgcn_fence(__ATOMIC_RELEASE, "agent");
;             asm volatile("s_waitcnt vmcnt(0)" ::: "memory");
;             const unsigned og = xb_add(&bar[XB_TOP], 1u);
;             const unsigned tg = og / nx;
;             if (og + 1u == (tg + 1u) * nx) xb_add(&bar[XB_TOPGEN], 1u);
;             else XB_SPIN(xb_ld(&bar[XB_TOPGEN]) == tg, bar);
;             __builtin_amdgcn_fence(__ATOMIC_ACQUIRE, "agent");
;             xb_add(&bar[XB_XGEN(b.x)], 1u);
;             asm volatile("s_waitcnt vmcnt(0)" ::: "memory");
;         } else {
;             XB_SPIN(xb_ld(&bar[XB_XGEN(b.x)]) == gen, bar);
;             __builtin_amdgcn_fence(__ATOMIC_ACQUIRE, "agent");
;             asm volatile("s_waitcnt vmcnt(0)" ::: "memory");
;         }
.LBB0_175:
	v_readlane_b32 s4, v248, 10
	s_lshl_b32 s4, s4, 8
	v_readlane_b32 s8, v248, 8
	v_readlane_b32 s9, v248, 9
	s_add_u32 s4, s8, s4
	s_addc_u32 s5, s9, 0
	v_mov_b32_e32 v3, 0x1000
	v_mov_b32_e32 v5, 1
	global_atomic_add v5, v3, v5, s[4:5] offset:1024 sc0
	v_cvt_f32_u32_e32 v3, v4
	v_sub_u32_e32 v6, 0, v4
	v_rcp_iflag_f32_e32 v3, v3
	s_nop 0
	v_mul_f32_e32 v3, 0x4f7ffffe, v3
	v_cvt_u32_f32_e32 v3, v3
	v_mul_lo_u32 v6, v6, v3
	v_mul_hi_u32 v6, v3, v6
	v_add_u32_e32 v3, v3, v6
	s_waitcnt vmcnt(0)
	v_mul_hi_u32 v3, v5, v3
	v_mul_lo_u32 v6, v3, v4
	v_sub_u32_e32 v6, v5, v6
	v_add_u32_e32 v7, 1, v3
	v_cmp_ge_u32_e32 vcc, v6, v4
	v_add_u32_e32 v5, 1, v5
	s_nop 0
	v_cndmask_b32_e32 v3, v3, v7, vcc
	v_sub_u32_e32 v7, v6, v4
	v_cndmask_b32_e32 v6, v6, v7, vcc
	v_add_u32_e32 v7, 1, v3
	v_cmp_ge_u32_e32 vcc, v6, v4
	s_nop 1
	v_cndmask_b32_e32 v3, v3, v7, vcc
	v_mul_lo_u32 v6, v4, v3
	v_add_u32_e32 v4, v6, v4
	v_cmp_ne_u32_e32 vcc, v5, v4
	s_and_saveexec_b64 s[8:9], vcc
	s_xor_b64 s[8:9], exec, s[8:9]
	s_cbranch_execz .LBB0_189
	s_waitcnt lgkmcnt(0)
	buffer_inv sc1
	v_mov_b32_e32 v2, 0x2000
	global_load_dword v2, v2, s[4:5] offset:1024 sc1
	s_add_u32 s14, s4, 0x2400
	s_addc_u32 s15, s5, 0
	s_waitcnt vmcnt(0)
	v_cmp_eq_u32_e32 vcc, v2, v3
	s_and_saveexec_b64 s[10:11], vcc
	s_cbranch_execz .LBB0_188
	s_add_u32 s12, s30, 0x3f52c200
	s_addc_u32 s13, s31, 0
	s_mov_b32 s27, 1
	s_mov_b64 s[16:17], 0
	v_mov_b32_e32 v2, 0
	s_branch .LBB0_179

; __device__ __forceinline__ unsigned xb_ld(unsigned* p)              { return __hip_atomic_load(p, __ATOMIC_RELAXED, __HIP_MEMORY_SCOPE_AGENT); }
; #define XB_SPIN(cond, bar) do { unsigned _sp = 0; while (cond) { __builtin_amdgcn_s_sleep(1); \
;     if ((++_sp & 255u) == 0u) { if (xb_ld(&(bar)[XB_TMO])) break; if (_sp > XB_SPIN_CAP) { atomicAdd(&(bar)[XB_TMO], 1u); break; } } } } while (0)
; __device__ __forceinline__ void xcd_barrier(const XcdBarrier& b) {
;     ...
;             XB_SPIN(xb_ld(&bar[XB_XGEN(b.x)]) == gen, bar);
;             __builtin_amdgcn_fence(__ATOMIC_ACQUIRE, "agent");
;             asm volatile("s_waitcnt vmcnt(0)" ::: "memory");
.LBB0_188:
	s_or_b64 exec, exec, s[10:11]
	s_waitcnt vmcnt(0)
	s_waitcnt vmcnt(0)

; __device__ __forceinline__ unsigned xb_ld(unsigned* p)              { return __hip_atomic_load(p, __ATOMIC_RELAXED, __HIP_MEMORY_SCOPE_AGENT); }
; __device__ __forceinline__ unsigned xb_add(unsigned* p, unsigned v) { return __hip_atomic_fetch_add(p, v, __ATOMIC_RELAXED, __HIP_MEMORY_SCOPE_AGENT); }
; #define XB_SPIN(cond, bar) do { unsigned _sp = 0; while (cond) { __builtin_amdgcn_s_sleep(1); \
;     if ((++_sp & 255u) == 0u) { if (xb_ld(&(bar)[XB_TMO])) break; if (_sp > XB_SPIN_CAP) { atomicAdd(&(bar)[XB_TMO], 1u); break; } } } } while (0)
; __device__ __forceinline__ void xcd_barrier(const XcdBarrier& b) {
;     ...
;         const unsigned old = xb_add(&bar[XB_XSUB(b.x)], 1u);
;         const unsigned gen = old / nloc;
;         if (old + 1u == (gen + 1u) * nloc) {
;             __builtin_amdgcn_fence(__ATOMIC_RELEASE, "agent");
;             asm volatile("s_waitcnt vmcnt(0)" ::: "memory");
;             const unsigned og = xb_add(&bar[XB_TOP], 1u);
;             const unsigned tg = og / nx;
;             if (og + 1u == (tg + 1u) * nx) xb_add(&bar[XB_TOPGEN], 1u);
;             else XB_SPIN(xb_ld(&bar[XB_TOPGEN]) == tg, bar);
;             __builtin_amdgcn_fence(__ATOMIC_ACQUIRE, "agent");
;             xb_add(&bar[XB_XGEN(b.x)], 1u);
;             asm volatile("s_waitcnt vmcnt(0)" ::: "memory");
;         } else {
;             XB_SPIN(xb_ld(&bar[XB_XGEN(b.x)]) == gen, bar);
;             __builtin_amdgcn_fence(__ATOMIC_ACQUIRE, "agent");
;             asm volatile("s_waitcnt vmcnt(0)" ::: "memory");
;         }
.LBB0_308:
	v_readlane_b32 s4, v248, 10
	s_lshl_b32 s4, s4, 8
	v_readlane_b32 s6, v248, 8
	v_readlane_b32 s7, v248, 9
	s_add_u32 s4, s6, s4
	s_addc_u32 s5, s7, 0
	v_mov_b32_e32 v3, 0x1000
	v_mov_b32_e32 v5, 1
	global_atomic_add v5, v3, v5, s[4:5] offset:1024 sc0
	v_cvt_f32_u32_e32 v3, v4
	v_sub_u32_e32 v6, 0, v4
	v_rcp_iflag_f32_e32 v3, v3
	s_nop 0
	v_mul_f32_e32 v3, 0x4f7ffffe, v3
	v_cvt_u32_f32_e32 v3, v3
	v_mul_lo_u32 v6, v6, v3
	v_mul_hi_u32 v6, v3, v6
	v_add_u32_e32 v3, v3, v6
	s_waitcnt vmcnt(0)
	v_mul_hi_u32 v3, v5, v3
	v_mul_lo_u32 v6, v3, v4
	v_sub_u32_e32 v6, v5, v6
	v_add_u32_e32 v7, 1, v3
	v_cmp_ge_u32_e32 vcc, v6, v4
	v_add_u32_e32 v5, 1, v5
	s_nop 0
	v_cndmask_b32_e32 v3, v3, v7, vcc
	v_sub_u32_e32 v7, v6, v4
	v_cndmask_b32_e32 v6, v6, v7, vcc
	v_add_u32_e32 v7, 1, v3
	v_cmp_ge_u32_e32 vcc, v6, v4
	s_nop 1
	v_cndmask_b32_e32 v3, v3, v7, vcc
	v_mul_lo_u32 v6, v4, v3
	v_add_u32_e32 v4, v6, v4
	v_cmp_ne_u32_e32 vcc, v5, v4
	s_and_saveexec_b64 s[6:7], vcc
	s_xor_b64 s[6:7], exec, s[6:7]
	s_cbranch_execz .LBB0_322
	s_waitcnt lgkmcnt(0)
	buffer_inv sc1
	v_mov_b32_e32 v2, 0x2000
	global_load_dword v2, v2, s[4:5] offset:1024 sc1
	s_add_u32 s14, s4, 0x2400
	s_addc_u32 s15, s5, 0
	s_waitcnt vmcnt(0)
	v_cmp_eq_u32_e32 vcc, v2, v3
	s_and_saveexec_b64 s[10:11], vcc
	s_cbranch_execz .LBB0_321
	s_add_u32 s12, s30, 0x3f52c200
	s_addc_u32 s13, s31, 0
	s_mov_b32 s27, 1
	s_mov_b64 s[16:17], 0
	v_mov_b32_e32 v2, 0
	s_branch .LBB0_312

; __device__ __forceinline__ unsigned xb_ld(unsigned* p)              { return __hip_atomic_load(p, __ATOMIC_RELAXED, __HIP_MEMORY_SCOPE_AGENT); }
; __device__ __forceinline__ unsigned xb_add(unsigned* p, unsigned v) { return __hip_atomic_fetch_add(p, v, __ATOMIC_RELAXED, __HIP_MEMORY_SCOPE_AGENT); }
; #define XB_SPIN(cond, bar) do { unsigned _sp = 0; while (cond) { __builtin_amdgcn_s_sleep(1); \
;     if ((++_sp & 255u) == 0u) { if (xb_ld(&(bar)[XB_TMO])) break; if (_sp > XB_SPIN_CAP) { atomicAdd(&(bar)[XB_TMO], 1u); break; } } } } while (0)
; __device__ __forceinline__ void xcd_barrier(const XcdBarrier& b) {
;     ...
;         const unsigned old = xb_add(&bar[XB_XSUB(b.x)], 1u);
;         const unsigned gen = old / nloc;
;         if (old + 1u == (gen + 1u) * nloc) {
;             __builtin_amdgcn_fence(__ATOMIC_RELEASE, "agent");
;             asm volatile("s_waitcnt vmcnt(0)" ::: "memory");
;             const unsigned og = xb_add(&bar[XB_TOP], 1u);
;             const unsigned tg = og / nx;
;             if (og + 1u == (tg + 1u) * nx) xb_add(&bar[XB_TOPGEN], 1u);
;             else XB_SPIN(xb_ld(&bar[XB_TOPGEN]) == tg, bar);
;             __builtin_amdgcn_fence(__ATOMIC_ACQUIRE, "agent");
;             xb_add(&bar[XB_XGEN(b.x)], 1u);
;             asm volatile("s_waitcnt vmcnt(0)" ::: "memory");
;         } else {
;             XB_SPIN(xb_ld(&bar[XB_XGEN(b.x)]) == gen, bar);
;             __builtin_amdgcn_fence(__ATOMIC_ACQUIRE, "agent");
;             asm volatile("s_waitcnt vmcnt(0)" ::: "memory");
;         }
.LBB0_706:
	v_readlane_b32 s4, v248, 10
	s_lshl_b32 s4, s4, 8
	v_readlane_b32 s6, v248, 8
	v_readlane_b32 s7, v248, 9
	s_add_u32 s4, s6, s4
	s_addc_u32 s5, s7, 0
	v_mov_b32_e32 v3, 0x1000
	v_mov_b32_e32 v5, 1
	global_atomic_add v5, v3, v5, s[4:5] offset:1024 sc0
	v_cvt_f32_u32_e32 v3, v4
	v_sub_u32_e32 v6, 0, v4
	v_rcp_iflag_f32_e32 v3, v3
	s_nop 0
	v_mul_f32_e32 v3, 0x4f7ffffe, v3
	v_cvt_u32_f32_e32 v3, v3
	v_mul_lo_u32 v6, v6, v3
	v_mul_hi_u32 v6, v3, v6
	v_add_u32_e32 v3, v3, v6
	s_waitcnt vmcnt(0)
	v_mul_hi_u32 v3, v5, v3
	v_mul_lo_u32 v6, v3, v4
	v_sub_u32_e32 v6, v5, v6
	v_add_u32_e32 v7, 1, v3
	v_cmp_ge_u32_e32 vcc, v6, v4
	v_add_u32_e32 v5, 1, v5
	s_nop 0
	v_cndmask_b32_e32 v3, v3, v7, vcc
	v_sub_u32_e32 v7, v6, v4
	v_cndmask_b32_e32 v6, v6, v7, vcc
	v_add_u32_e32 v7, 1, v3
	v_cmp_ge_u32_e32 vcc, v6, v4
	s_nop 1
	v_cndmask_b32_e32 v3, v3, v7, vcc
	v_mul_lo_u32 v6, v4, v3
	v_add_u32_e32 v4, v6, v4
	v_cmp_ne_u32_e32 vcc, v5, v4
	s_and_saveexec_b64 s[6:7], vcc
	s_xor_b64 s[6:7], exec, s[6:7]
	s_cbranch_execz .LBB0_720
	s_waitcnt lgkmcnt(0)
	buffer_inv sc1
	v_mov_b32_e32 v2, 0x2000
	global_load_dword v2, v2, s[4:5] offset:1024 sc1
	s_add_u32 s12, s4, 0x2400
	s_addc_u32 s13, s5, 0
	s_waitcnt vmcnt(0)
	v_cmp_eq_u32_e32 vcc, v2, v3
	s_and_saveexec_b64 s[8:9], vcc
	s_cbranch_execz .LBB0_719
	s_add_u32 s10, s30, 0x3f52c200
	s_addc_u32 s11, s31, 0
	s_mov_b32 s24, 1
	s_mov_b64 s[14:15], 0
	v_mov_b32_e32 v2, 0
	s_branch .LBB0_710

; __device__ __forceinline__ unsigned xb_ld(unsigned* p)              { return __hip_atomic_load(p, __ATOMIC_RELAXED, __HIP_MEMORY_SCOPE_AGENT); }
; __device__ __forceinline__ unsigned xb_add(unsigned* p, unsigned v) { return __hip_atomic_fetch_add(p, v, __ATOMIC_RELAXED, __HIP_MEMORY_SCOPE_AGENT); }
; #define XB_SPIN(cond, bar) do { unsigned _sp = 0; while (cond) { __builtin_amdgcn_s_sleep(1); \
;     if ((++_sp & 255u) == 0u) { if (xb_ld(&(bar)[XB_TMO])) break; if (_sp > XB_SPIN_CAP) { atomicAdd(&(bar)[XB_TMO], 1u); break; } } } } while (0)
; __device__ __forceinline__ void xcd_barrier(const XcdBarrier& b) {
;     ...
;         const unsigned old = xb_add(&bar[XB_XSUB(b.x)], 1u);
;         const unsigned gen = old / nloc;
;         if (old + 1u == (gen + 1u) * nloc) {
;             __builtin_amdgcn_fence(__ATOMIC_RELEASE, "agent");
;             asm volatile("s_waitcnt vmcnt(0)" ::: "memory");
;             const unsigned og = xb_add(&bar[XB_TOP], 1u);
;             const unsigned tg = og / nx;
;             if (og + 1u == (tg + 1u) * nx) xb_add(&bar[XB_TOPGEN], 1u);
;             else XB_SPIN(xb_ld(&bar[XB_TOPGEN]) == tg, bar);
;             __builtin_amdgcn_fence(__ATOMIC_ACQUIRE, "agent");
;             xb_add(&bar[XB_XGEN(b.x)], 1u);
;             asm volatile("s_waitcnt vmcnt(0)" ::: "memory");
;         } else {
;             XB_SPIN(xb_ld(&bar[XB_XGEN(b.x)]) == gen, bar);
;             __builtin_amdgcn_fence(__ATOMIC_ACQUIRE, "agent");
;             asm volatile("s_waitcnt vmcnt(0)" ::: "memory");
;         }
.LBB0_845:
	v_readlane_b32 s4, v248, 10
	s_lshl_b32 s4, s4, 8
	v_readlane_b32 s6, v248, 8
	v_readlane_b32 s7, v248, 9
	s_add_u32 s4, s6, s4
	s_addc_u32 s5, s7, 0
	v_mov_b32_e32 v3, 0x1000
	v_mov_b32_e32 v5, 1
	global_atomic_add v5, v3, v5, s[4:5] offset:1024 sc0
	v_cvt_f32_u32_e32 v3, v4
	v_sub_u32_e32 v6, 0, v4
	v_rcp_iflag_f32_e32 v3, v3
	s_nop 0
	v_mul_f32_e32 v3, 0x4f7ffffe, v3
	v_cvt_u32_f32_e32 v3, v3
	v_mul_lo_u32 v6, v6, v3
	v_mul_hi_u32 v6, v3, v6
	v_add_u32_e32 v3, v3, v6
	s_waitcnt vmcnt(0)
	v_mul_hi_u32 v3, v5, v3
	v_mul_lo_u32 v6, v3, v4
	v_sub_u32_e32 v6, v5, v6
	v_add_u32_e32 v7, 1, v3
	v_cmp_ge_u32_e32 vcc, v6, v4
	v_add_u32_e32 v5, 1, v5
	s_nop 0
	v_cndmask_b32_e32 v3, v3, v7, vcc
	v_sub_u32_e32 v7, v6, v4
	v_cndmask_b32_e32 v6, v6, v7, vcc
	v_add_u32_e32 v7, 1, v3
	v_cmp_ge_u32_e32 vcc, v6, v4
	s_nop 1
	v_cndmask_b32_e32 v3, v3, v7, vcc
	v_mul_lo_u32 v6, v4, v3
	v_add_u32_e32 v4, v6, v4
	v_cmp_ne_u32_e32 vcc, v5, v4
	s_and_saveexec_b64 s[6:7], vcc
	s_xor_b64 s[6:7], exec, s[6:7]
	s_cbranch_execz .LBB0_859
	s_waitcnt lgkmcnt(0)
	buffer_inv sc1
	v_mov_b32_e32 v2, 0x2000
	global_load_dword v2, v2, s[4:5] offset:1024 sc1
	s_add_u32 s12, s4, 0x2400
	s_addc_u32 s13, s5, 0
	s_waitcnt vmcnt(0)
	v_cmp_eq_u32_e32 vcc, v2, v3
	s_and_saveexec_b64 s[8:9], vcc
	s_cbranch_execz .LBB0_858
	s_add_u32 s10, s30, 0x3f52c200
	s_addc_u32 s11, s31, 0
	s_mov_b32 s27, 1
	s_mov_b64 s[14:15], 0
	v_mov_b32_e32 v2, 0
	s_branch .LBB0_849

; __device__ __forceinline__ unsigned xb_ld(unsigned* p)              { return __hip_atomic_load(p, __ATOMIC_RELAXED, __HIP_MEMORY_SCOPE_AGENT); }
; __device__ __forceinline__ unsigned xb_add(unsigned* p, unsigned v) { return __hip_atomic_fetch_add(p, v, __ATOMIC_RELAXED, __HIP_MEMORY_SCOPE_AGENT); }
; #define XB_SPIN(cond, bar) do { unsigned _sp = 0; while (cond) { __builtin_amdgcn_s_sleep(1); \
;     if ((++_sp & 255u) == 0u) { if (xb_ld(&(bar)[XB_TMO])) break; if (_sp > XB_SPIN_CAP) { atomicAdd(&(bar)[XB_TMO], 1u); break; } } } } while (0)
; __device__ __forceinline__ void xcd_barrier(const XcdBarrier& b) {
;     ...
;         const unsigned old = xb_add(&bar[XB_XSUB(b.x)], 1u);
;         const unsigned gen = old / nloc;
;         if (old + 1u == (gen + 1u) * nloc) {
;             __builtin_amdgcn_fence(__ATOMIC_RELEASE, "agent");
;             asm volatile("s_waitcnt vmcnt(0)" ::: "memory");
;             const unsigned og = xb_add(&bar[XB_TOP], 1u);
;             const unsigned tg = og / nx;
;             if (og + 1u == (tg + 1u) * nx) xb_add(&bar[XB_TOPGEN], 1u);
;             else XB_SPIN(xb_ld(&bar[XB_TOPGEN]) == tg, bar);
;             __builtin_amdgcn_fence(__ATOMIC_ACQUIRE, "agent");
;             xb_add(&bar[XB_XGEN(b.x)], 1u);
;             asm volatile("s_waitcnt vmcnt(0)" ::: "memory");
;         } else {
;             XB_SPIN(xb_ld(&bar[XB_XGEN(b.x)]) == gen, bar);
;             __builtin_amdgcn_fence(__ATOMIC_ACQUIRE, "agent");
;             asm volatile("s_waitcnt vmcnt(0)" ::: "memory");
;         }
.LBB0_2262:
	v_readlane_b32 s2, v248, 10
	s_lshl_b32 s2, s2, 8
	v_readlane_b32 s4, v248, 8
	v_readlane_b32 s5, v248, 9
	s_add_u32 s2, s4, s2
	s_addc_u32 s3, s5, 0
	v_mov_b32_e32 v3, 0x1000
	v_mov_b32_e32 v5, 1
	global_atomic_add v5, v3, v5, s[2:3] offset:1024 sc0
	v_cvt_f32_u32_e32 v3, v4
	v_sub_u32_e32 v6, 0, v4
	v_rcp_iflag_f32_e32 v3, v3
	s_nop 0
	v_mul_f32_e32 v3, 0x4f7ffffe, v3
	v_cvt_u32_f32_e32 v3, v3
	v_mul_lo_u32 v6, v6, v3
	v_mul_hi_u32 v6, v3, v6
	v_add_u32_e32 v3, v3, v6
	s_waitcnt vmcnt(0)
	v_mul_hi_u32 v3, v5, v3
	v_mul_lo_u32 v6, v3, v4
	v_sub_u32_e32 v6, v5, v6
	v_add_u32_e32 v7, 1, v3
	v_cmp_ge_u32_e32 vcc, v6, v4
	v_add_u32_e32 v5, 1, v5
	s_nop 0
	v_cndmask_b32_e32 v3, v3, v7, vcc
	v_sub_u32_e32 v7, v6, v4
	v_cndmask_b32_e32 v6, v6, v7, vcc
	v_add_u32_e32 v7, 1, v3
	v_cmp_ge_u32_e32 vcc, v6, v4
	s_nop 1
	v_cndmask_b32_e32 v3, v3, v7, vcc
	v_mul_lo_u32 v6, v4, v3
	v_add_u32_e32 v4, v6, v4
	v_cmp_ne_u32_e32 vcc, v5, v4
	s_and_saveexec_b64 s[4:5], vcc
	s_xor_b64 s[4:5], exec, s[4:5]
	s_cbranch_execz .LBB0_2276
	s_waitcnt lgkmcnt(0)
	buffer_inv sc1
	v_mov_b32_e32 v2, 0x2000
	global_load_dword v2, v2, s[2:3] offset:1024 sc1
	s_add_u32 s12, s2, 0x2400
	s_addc_u32 s13, s3, 0
	s_waitcnt vmcnt(0)
	v_cmp_eq_u32_e32 vcc, v2, v3
	s_and_saveexec_b64 s[8:9], vcc
	s_cbranch_execz .LBB0_2275
	s_add_u32 s10, s30, 0x3f52c200
	s_addc_u32 s11, s31, 0
	s_mov_b32 s24, 1
	s_mov_b64 s[14:15], 0
	v_mov_b32_e32 v2, 0
	s_branch .LBB0_2266
